# finalize_sample (layer-0 residual/hi-lo step run by the sample blocks at phase B of layer 1): its ~26 dependent load-wait rounds become all loads in flight with one wait
# speedup vs baseline: 1.0715x; 1.0072x over previous
.LBB0_373:
	s_and_b64 vcc, exec, s[0:1]
	s_cbranch_vccz .LBB0_516
	v_readlane_b32 s0, v234, 59
	v_readlane_b32 s1, v234, 60
	v_readlane_b32 s28, v235, 22
	s_andn2_b64 vcc, exec, s[0:1]
	v_readlane_b32 s29, v235, 23
	v_readlane_b32 s11, v235, 31
	v_readlane_b32 s36, v235, 32
	s_cbranch_vccnz .LBB0_384
	s_nop 0
	s_nop 0
	s_nop 0
	s_nop 0
	s_nop 0
	s_nop 0
	s_nop 0
	s_nop 0
	s_nop 0
	s_nop 0
	s_nop 0
	s_nop 0
	s_nop 0
	v_mov_b32_e32 v0, v194
	v_readlane_b32 s1, v234, 44
	v_readfirstlane_b32 s0, v0
	s_ashr_i32 s0, s0, 6
	s_add_i32 s4, s0, s1
	s_ashr_i32 s5, s4, 31
	v_mov_b32_e32 v0, v194
	s_add_i32 s0, s4, 0x4000
	s_lshl_b64 s[8:9], s[4:5], 12
	s_mov_b32 s7, s15
	s_mov_b32 s6, s14
	s_add_u32 s34, s33, s8
	v_and_b32_e32 v22, 63, v0
	v_readlane_b32 s12, v237, 22
	s_addc_u32 s35, s90, s9
	v_readlane_b32 s16, v237, 26
	v_lshlrev_b32_e32 v172, 4, v22
	v_lshl_add_u64 v[8:9], s[34:35], 0, v[172:173]
	s_mov_b32 s16, 0x100000
	v_add_co_u32_e32 v10, vcc, s16, v8
	global_load_dwordx4 v[0:3], v172, s[34:35]
	s_nop 0
	v_addc_co_u32_e32 v11, vcc, 0, v9, vcc
	global_load_dwordx4 v[4:7], v[10:11], off
	s_mov_b32 s16, 0x200000
	v_add_co_u32_e32 v16, vcc, s16, v8
	s_mov_b32 s16, 0x300000
	s_nop 0
	v_addc_co_u32_e32 v17, vcc, 0, v9, vcc
	v_add_co_u32_e32 v20, vcc, s16, v8
	s_mov_b32 s16, 0x400000
	s_nop 0
	v_addc_co_u32_e32 v21, vcc, 0, v9, vcc
	v_add_co_u32_e32 v18, vcc, s16, v8
	s_mov_b32 s16, 0x500000
	s_nop 0
	v_addc_co_u32_e32 v19, vcc, 0, v9, vcc
	v_add_co_u32_e32 v12, vcc, s16, v8
	s_ashr_i32 s1, s0, 31
	s_nop 0
	v_addc_co_u32_e32 v13, vcc, 0, v9, vcc
	s_lshl_b64 s[4:5], s[0:1], 12
	s_add_u32 s4, s84, s4
	s_addc_u32 s5, s85, s5
	v_readlane_b32 s14, v237, 24
	v_readlane_b32 s15, v237, 25
	s_add_u32 s8, s14, s8
	s_addc_u32 s9, s15, s9
	v_readlane_b32 s13, v237, 23
	v_readlane_b32 s17, v237, 27
	v_readlane_b32 s18, v237, 28
	v_readlane_b32 s19, v237, 29
	v_readlane_b32 s20, v237, 30
	v_readlane_b32 s21, v237, 31
	v_readlane_b32 s22, v237, 32
	v_readlane_b32 s23, v237, 33
	v_readlane_b32 s24, v237, 34
	v_readlane_b32 s25, v237, 35
	v_readlane_b32 s26, v237, 36
	v_readlane_b32 s27, v237, 37
	global_load_dwordx4 v[32:35], v[16:17], off
	global_load_dwordx4 v[36:39], v[20:21], off
	global_load_dwordx4 v[40:43], v[18:19], off
	global_load_dwordx4 v[44:47], v[12:13], off
	global_load_dwordx4 v[48:51], v172, s[8:9]
	global_load_dwordx4 v[52:55], v172, s[34:35] offset:1024
	global_load_dwordx4 v[56:59], v[10:11], off offset:1024
	global_load_dwordx4 v[60:63], v[16:17], off offset:1024
	global_load_dwordx4 v[64:67], v[20:21], off offset:1024
	global_load_dwordx4 v[68:71], v[18:19], off offset:1024
	global_load_dwordx4 v[72:75], v[12:13], off offset:1024
	global_load_dwordx4 v[76:79], v172, s[8:9] offset:1024
	global_load_dwordx4 v[80:83], v172, s[34:35] offset:2048
	global_load_dwordx4 v[84:87], v[10:11], off offset:2048
	global_load_dwordx4 v[88:91], v[16:17], off offset:2048
	global_load_dwordx4 v[92:95], v[20:21], off offset:2048
	global_load_dwordx4 v[96:99], v[18:19], off offset:2048
	global_load_dwordx4 v[100:103], v[12:13], off offset:2048
	global_load_dwordx4 v[104:107], v172, s[8:9] offset:2048
	global_load_dwordx4 v[108:111], v172, s[34:35] offset:3072
	global_load_dwordx4 v[112:115], v[10:11], off offset:3072
	global_load_dwordx4 v[116:119], v[16:17], off offset:3072
	global_load_dwordx4 v[120:123], v[20:21], off offset:3072
	global_load_dwordx4 v[124:127], v[18:19], off offset:3072
	global_load_dwordx4 v[136:139], v[12:13], off offset:3072
	global_load_dwordx4 v[140:143], v172, s[8:9] offset:3072
	s_waitcnt vmcnt(0)
	v_pk_add_f32 v[6:7], v[2:3], v[6:7]
	v_pk_add_f32 v[4:5], v[0:1], v[4:5]
	v_pk_add_f32 v[6:7], v[6:7], v[34:35]
	v_pk_add_f32 v[4:5], v[4:5], v[32:33]
	v_pk_add_f32 v[6:7], v[6:7], v[38:39]
	v_pk_add_f32 v[4:5], v[4:5], v[36:37]
	v_pk_add_f32 v[6:7], v[6:7], v[42:43]
	v_pk_add_f32 v[4:5], v[4:5], v[40:41]
	v_pk_add_f32 v[6:7], v[6:7], v[46:47]
	v_pk_add_f32 v[8:9], v[4:5], v[44:45]
	v_pk_add_f32 v[0:1], v[6:7], v[50:51]
	v_pk_add_f32 v[2:3], v[8:9], v[48:49]
	v_pk_add_f32 v[8:9], v[54:55], v[58:59]
	v_pk_add_f32 v[14:15], v[52:53], v[56:57]
	v_mul_f32_e32 v23, v3, v3
	v_fmac_f32_e32 v23, v2, v2
	v_fmac_f32_e32 v23, v0, v0
	v_fmac_f32_e32 v23, v1, v1
	v_pk_add_f32 v[8:9], v[8:9], v[62:63]
	v_pk_add_f32 v[14:15], v[14:15], v[60:61]
	v_pk_add_f32 v[8:9], v[8:9], v[66:67]
	v_pk_add_f32 v[14:15], v[14:15], v[64:65]
	v_pk_add_f32 v[8:9], v[8:9], v[70:71]
	v_pk_add_f32 v[14:15], v[14:15], v[68:69]
	v_pk_add_f32 v[24:25], v[8:9], v[74:75]
	v_pk_add_f32 v[14:15], v[14:15], v[72:73]
	v_pk_add_f32 v[4:5], v[24:25], v[78:79]
	v_pk_add_f32 v[6:7], v[14:15], v[76:77]
	v_pk_add_f32 v[14:15], v[80:81], v[84:85]
	v_mul_f32_e32 v8, v7, v7
	v_fmac_f32_e32 v8, v6, v6
	v_fmac_f32_e32 v8, v4, v4
	v_fmac_f32_e32 v8, v5, v5
	v_add_f32_e32 v23, v23, v8
	v_pk_add_f32 v[8:9], v[82:83], v[86:87]
	v_pk_add_f32 v[8:9], v[8:9], v[90:91]
	v_pk_add_f32 v[14:15], v[14:15], v[88:89]
	v_pk_add_f32 v[8:9], v[8:9], v[94:95]
	v_pk_add_f32 v[14:15], v[14:15], v[92:93]
	v_pk_add_f32 v[8:9], v[8:9], v[98:99]
	v_pk_add_f32 v[14:15], v[14:15], v[96:97]
	v_pk_add_f32 v[8:9], v[8:9], v[102:103]
	v_pk_add_f32 v[14:15], v[14:15], v[100:101]
	v_pk_add_f32 v[14:15], v[14:15], v[104:105]
	s_nop 0
	v_mul_f32_e32 v24, v15, v15
	v_pk_add_f32 v[8:9], v[8:9], v[106:107]
	v_fmac_f32_e32 v24, v14, v14
	v_fmac_f32_e32 v24, v8, v8
	v_fmac_f32_e32 v24, v9, v9
	v_add_f32_e32 v23, v23, v24
	v_pk_add_f32 v[10:11], v[110:111], v[114:115]
	v_pk_add_f32 v[28:29], v[108:109], v[112:113]
	v_pk_add_f32 v[10:11], v[10:11], v[118:119]
	v_pk_add_f32 v[16:17], v[28:29], v[116:117]
	v_pk_add_f32 v[20:21], v[16:17], v[120:121]
	v_pk_add_f32 v[10:11], v[10:11], v[122:123]
	v_pk_add_f32 v[20:21], v[20:21], v[124:125]
	v_pk_add_f32 v[10:11], v[10:11], v[126:127]
	v_pk_add_f32 v[10:11], v[10:11], v[138:139]
	v_pk_add_f32 v[12:13], v[20:21], v[136:137]
	v_lshlrev_b32_e32 v20, 3, v22
	v_mov_b32_e32 v16, v140
	v_mov_b32_e32 v17, v141
	v_mov_b32_e32 v18, v142
	v_mov_b32_e32 v19, v143
	v_mov_b32_e32 v24, v120
	v_mov_b32_e32 v25, v121
	v_mov_b32_e32 v26, v122
	v_mov_b32_e32 v27, v123
	v_mov_b32_e32 v30, v114
	v_mov_b32_e32 v31, v115
	v_pk_add_f32 v[12:13], v[12:13], v[16:17]
	v_pk_add_f32 v[18:19], v[10:11], v[18:19]
	v_mul_f32_e32 v10, v13, v13
	v_and_b32_e32 v11, 64, v195
	v_fmac_f32_e32 v10, v12, v12
	v_add_u32_e32 v11, 64, v11
	v_xor_b32_e32 v16, 32, v195
	v_fmac_f32_e32 v10, v18, v18
	v_cmp_lt_i32_e32 vcc, v16, v11
	v_fmac_f32_e32 v10, v19, v19
	v_add_f32_e32 v10, v23, v10
	v_cndmask_b32_e32 v16, v195, v16, vcc
	v_lshlrev_b32_e32 v16, 2, v16
	ds_bpermute_b32 v16, v16, v10
	v_cvt_pk_bf16_f32 v17, v0, v1
	s_waitcnt lgkmcnt(0)
	v_add_f32_e32 v10, v10, v16
	v_xor_b32_e32 v16, 16, v195
	v_cmp_lt_i32_e32 vcc, v16, v11
	s_nop 1
	v_cndmask_b32_e32 v16, v195, v16, vcc
	v_lshlrev_b32_e32 v16, 2, v16
	ds_bpermute_b32 v16, v16, v10
	s_waitcnt lgkmcnt(0)
	v_add_f32_e32 v10, v10, v16
	v_xor_b32_e32 v16, 8, v195
	v_cmp_lt_i32_e32 vcc, v16, v11
	s_nop 1
	v_cndmask_b32_e32 v16, v195, v16, vcc
	v_lshlrev_b32_e32 v16, 2, v16
	ds_bpermute_b32 v16, v16, v10
	s_waitcnt lgkmcnt(0)
	v_add_f32_e32 v10, v10, v16
	v_xor_b32_e32 v16, 4, v195
	v_cmp_lt_i32_e32 vcc, v16, v11
	s_nop 1
	v_cndmask_b32_e32 v16, v195, v16, vcc
	v_lshlrev_b32_e32 v16, 2, v16
	ds_bpermute_b32 v16, v16, v10
	s_waitcnt lgkmcnt(0)
	v_add_f32_e32 v10, v10, v16
	v_xor_b32_e32 v16, 2, v195
	v_cmp_lt_i32_e32 vcc, v16, v11
	s_nop 1
	v_cndmask_b32_e32 v16, v195, v16, vcc
	v_lshlrev_b32_e32 v16, 2, v16
	ds_bpermute_b32 v16, v16, v10
	s_waitcnt lgkmcnt(0)
	v_add_f32_e32 v10, v10, v16
	v_xor_b32_e32 v16, 1, v195
	v_cmp_lt_i32_e32 vcc, v16, v11
	s_nop 1
	v_cndmask_b32_e32 v11, v195, v16, vcc
	v_cvt_pk_bf16_f32 v16, v2, v3
	v_lshlrev_b32_e32 v11, 2, v11
	v_lshlrev_b32_e32 v21, 16, v16
	v_sub_f32_e32 v2, v2, v21
	v_and_b32_e32 v21, 0xffff0000, v16
	v_sub_f32_e32 v3, v3, v21
	v_cvt_pk_bf16_f32 v2, v2, v3
	v_lshlrev_b32_e32 v3, 16, v17
	v_sub_f32_e32 v0, v0, v3
	v_and_b32_e32 v3, 0xffff0000, v17
	v_sub_f32_e32 v1, v1, v3
	v_cvt_pk_bf16_f32 v3, v0, v1
	global_store_dwordx2 v20, v[16:17], s[4:5]
	global_store_dwordx2 v20, v[2:3], s[4:5] offset:2048
	v_cvt_pk_bf16_f32 v0, v6, v7
	v_cvt_pk_bf16_f32 v1, v4, v5
	ds_bpermute_b32 v11, v11, v10
	v_lshlrev_b32_e32 v2, 16, v0
	v_and_b32_e32 v3, 0xffff0000, v0
	v_sub_f32_e32 v2, v6, v2
	v_sub_f32_e32 v3, v7, v3
	v_cvt_pk_bf16_f32 v2, v2, v3
	v_lshlrev_b32_e32 v3, 16, v1
	v_sub_f32_e32 v3, v4, v3
	v_and_b32_e32 v4, 0xffff0000, v1
	v_sub_f32_e32 v4, v5, v4
	v_cvt_pk_bf16_f32 v3, v3, v4
	global_store_dwordx2 v20, v[0:1], s[4:5] offset:512
	global_store_dwordx2 v20, v[2:3], s[4:5] offset:2560
	v_cvt_pk_bf16_f32 v0, v14, v15
	v_cvt_pk_bf16_f32 v1, v8, v9
	v_cmp_eq_u32_e32 vcc, 0, v22
	v_lshlrev_b32_e32 v2, 16, v0
	v_and_b32_e32 v3, 0xffff0000, v0
	v_sub_f32_e32 v2, v14, v2
	v_sub_f32_e32 v3, v15, v3
	v_cvt_pk_bf16_f32 v2, v2, v3
	v_lshlrev_b32_e32 v3, 16, v1
	v_sub_f32_e32 v3, v8, v3
	v_and_b32_e32 v4, 0xffff0000, v1
	v_sub_f32_e32 v4, v9, v4
	v_cvt_pk_bf16_f32 v3, v3, v4
	global_store_dwordx2 v20, v[0:1], s[4:5] offset:1024
	global_store_dwordx2 v20, v[2:3], s[4:5] offset:3072
	v_cvt_pk_bf16_f32 v0, v12, v13
	v_cvt_pk_bf16_f32 v1, v18, v19
	s_nop 0
	v_lshlrev_b32_e32 v2, 16, v0
	v_and_b32_e32 v3, 0xffff0000, v0
	v_sub_f32_e32 v2, v12, v2
	v_sub_f32_e32 v3, v13, v3
	v_cvt_pk_bf16_f32 v2, v2, v3
	v_lshlrev_b32_e32 v3, 16, v1
	v_sub_f32_e32 v3, v18, v3
	v_and_b32_e32 v4, 0xffff0000, v1
	v_sub_f32_e32 v4, v19, v4
	v_cvt_pk_bf16_f32 v3, v3, v4
	global_store_dwordx2 v20, v[0:1], s[4:5] offset:1536
	global_store_dwordx2 v20, v[2:3], s[4:5] offset:3584
	s_and_saveexec_b64 s[4:5], vcc
	s_cbranch_execz .LBB0_377
	s_lshl_b64 s[0:1], s[0:1], 2
	s_add_u32 s0, s64, s0
	s_addc_u32 s1, s65, s1
	s_waitcnt lgkmcnt(0)
	v_add_f32_e32 v0, v10, v11
	global_store_dword v173, v0, s[0:1]
